# barrier 1 of the attention half-step moved two MFMAs later (only the two V staging writes follow it now)
# baseline (speedup 1.0000x reference)
; __device__ __forceinline__ void partialSM(f32x16& p0, f32x16& p1, float& m_reg, float& mn, float& alpha) {
;     float pmax = p0[0]; for (int r = 1; r < 16; ++r) pmax = fmaxf(pmax, p0[r]); for (int r = 0; r < 16; ++r) pmax = fmaxf(pmax, p1[r]);
;     { auto rr = __builtin_amdgcn_permlane32_swap(__float_as_uint(pmax), __float_as_uint(pmax), false, false);
;       pmax = fmaxf(__uint_as_float(rr[0]), __uint_as_float(rr[1])); }
;     constexpr float C2 = 1.4426950408889634f * SCALE;
;     if (__builtin_expect(__all((pmax - m_reg) * SCALE <= THR), 1)) { mn = m_reg; alpha = 1.f; }
;     else { mn = fmaxf(m_reg, pmax); alpha = __builtin_amdgcn_exp2f((m_reg - mn) * C2); m_reg = mn; }
;     const float mnL = -mn * C2;
;     for (int r = 0; r < 16; ++r) p0[r] = fmaf(p0[r], C2, mnL); for (int r = 0; r < 16; ++r) p1[r] = fmaf(p1[r], C2, mnL);
;     for (int r = 0; r < 16; ++r) p0[r] = __builtin_amdgcn_exp2f(p0[r]);
; }
; __device__ __forceinline__ void finishSM(f32x16& p0, f32x16& p1, float alpha, float& l_reg, bf16x8& pa0, bf16x8& pa1, bf16x8& pa2, bf16x8& pa3) {
;     for (int r = 0; r < 16; ++r) p1[r] = __builtin_amdgcn_exp2f(p1[r]);
;     float ps = 0; for (int r = 0; r < 16; ++r) ps += p0[r]; for (int r = 0; r < 16; ++r) ps += p1[r];
;     { auto rr = __builtin_amdgcn_permlane32_swap(__float_as_uint(ps), __float_as_uint(ps), false, false);
;       ps = __uint_as_float(rr[0]) + __uint_as_float(rr[1]); }
;     l_reg = l_reg * alpha + ps;
;     ...
;     PK4(p0, 0, pa0); PK4(p0, 8, pa1); PK4(p1, 0, pa2); PK4(p1, 8, pa3);
;     ...
; }
; template <int KB, bool SK>
; __device__ __forceinline__ void qkt(f32x16& p0, f32x16& p1, const char* K_lds, int r32, int hi, const bf16x8* qr, bool act) {
;     if (SK && !act) { const float NEG = -__builtin_inff();
; #pragma unroll
;         for (int r = 0; r < 16; ++r) { p0[r] = NEG; p1[r] = NEG; } return; }
;     p0 = f32x16{}; p1 = f32x16{};
;     const char* kb[4];
; #pragma unroll
;     for (int dd = 0; dd < 4; ++dd) kb[dd] = K_lds + KB * SHM_K + KSWZ(r32, (dd * 16 + hi * 8) * 2);
; #pragma unroll
;     for (int d0 = 0; d0 < 8; ++d0) { const char* a = kb[d0 & 3] + (d0 >> 2) * 128;
;         bf16x8 b0 = *reinterpret_cast<const bf16x8*>(a);
;         bf16x8 b1 = *reinterpret_cast<const bf16x8*>(a + 32 * 256);
;         const bf16x8 qf = qr[d0];
;         p0 = __builtin_amdgcn_mfma_f32_32x32x16_bf16(b0, qf, p0, 0, 0, 0);
.Lh1_back:
	v_fmamk_f32 v228, v86, 0x3e0293ee, v253
	v_fmamk_f32 v229, v87, 0x3e0293ee, v253
	s_waitcnt lgkmcnt(12)
	v_mfma_f32_32x32x16_bf16 v[50:65], v[66:69], v[186:189], v[50:65]
	ds_read_b64_tr_b16 v[182:183], v202 offset:0x600
	ds_read_b64_tr_b16 v[184:185], v202 offset:0xe00
	v_fmamk_f32 v230, v88, 0x3e0293ee, v253
	v_fmamk_f32 v231, v89, 0x3e0293ee, v253
	v_fmamk_f32 v232, v90, 0x3e0293ee, v253
	s_waitcnt lgkmcnt(12)
	v_mfma_f32_32x32x16_bf16 v[50:65], v[106:109], v[190:193], v[50:65]
	ds_read_b64_tr_b16 v[186:187], v202 offset:0x1600
	ds_read_b64_tr_b16 v[188:189], v202 offset:0x1e00
	v_fmamk_f32 v233, v91, 0x3e0293ee, v253
	v_fmamk_f32 v234, v92, 0x3e0293ee, v253
	v_fmamk_f32 v235, v93, 0x3e0293ee, v253
	s_waitcnt lgkmcnt(12)
	v_mfma_f32_32x32x16_bf16 v[50:65], v[110:113], v[244:247], v[50:65]
	ds_read_b64_tr_b16 v[190:191], v202 offset:0x2600
	ds_read_b64_tr_b16 v[192:193], v202 offset:0x2e00
	v_fmamk_f32 v236, v94, 0x3e0293ee, v253
	v_fmamk_f32 v237, v95, 0x3e0293ee, v253
	v_fmamk_f32 v238, v96, 0x3e0293ee, v253
	s_waitcnt lgkmcnt(12)
	v_mfma_f32_32x32x16_bf16 v[18:33], v[102:105], v[114:117], v[18:33]
	ds_read_b64_tr_b16 v[244:245], v202 offset:0x3600
	ds_read_b64_tr_b16 v[246:247], v202 offset:0x3e00
	v_fmamk_f32 v239, v97, 0x3e0293ee, v253
	v_fmamk_f32 v98, v98, 0x3e0293ee, v253
	v_fmamk_f32 v99, v99, 0x3e0293ee, v253
	s_waitcnt lgkmcnt(12)
	v_mfma_f32_32x32x16_bf16 v[18:33], v[66:69], v[118:121], v[18:33]
	v_fmamk_f32 v100, v100, 0x3e0293ee, v253
	v_fmamk_f32 v101, v101, 0x3e0293ee, v253
	v_fmamk_f32 v86, v70, 0x3e0293ee, v253
	s_waitcnt lgkmcnt(10)
	v_mfma_f32_32x32x16_bf16 v[18:33], v[106:109], v[122:125], v[18:33]
	v_fmamk_f32 v95, v71, 0x3e0293ee, v253
	v_fmamk_f32 v96, v72, 0x3e0293ee, v253
	v_fmamk_f32 v97, v73, 0x3e0293ee, v253
	s_waitcnt lgkmcnt(8)
	v_mfma_f32_32x32x16_bf16 v[18:33], v[110:113], v[126:129], v[18:33]
	v_fmamk_f32 v179, v74, 0x3e0293ee, v253
	v_fmamk_f32 v87, v75, 0x3e0293ee, v253
	v_fmamk_f32 v88, v76, 0x3e0293ee, v253
	s_waitcnt lgkmcnt(6)
	v_mfma_f32_32x32x16_bf16 v[2:17], v[102:105], v[182:185], v[2:17]
	v_fmamk_f32 v89, v77, 0x3e0293ee, v253
	v_fmamk_f32 v90, v78, 0x3e0293ee, v253
	v_fmamk_f32 v91, v79, 0x3e0293ee, v253
	s_waitcnt lgkmcnt(4)
	v_mfma_f32_32x32x16_bf16 v[2:17], v[66:69], v[186:189], v[2:17]
	v_fmamk_f32 v92, v80, 0x3e0293ee, v253
	v_fmamk_f32 v93, v81, 0x3e0293ee, v253
	v_fmamk_f32 v94, v82, 0x3e0293ee, v253
	s_waitcnt lgkmcnt(0)
	s_barrier
	s_waitcnt vmcnt(0)
	v_mfma_f32_32x32x16_bf16 v[2:17], v[106:109], v[190:193], v[2:17]
	ds_write_b128 v209, v[162:165]
	v_fmamk_f32 v180, v83, 0x3e0293ee, v253
	v_fmamk_f32 v181, v84, 0x3e0293ee, v253
	v_fmamk_f32 v178, v85, 0x3e0293ee, v253
	v_mfma_f32_32x32x16_bf16 v[2:17], v[110:113], v[244:247], v[2:17]
	ds_write_b128 v210, v[166:169]
	s_and_b64 vcc, exec, s[4:5]
	s_cbranch_vccnz .Lh1_noresc
	s_and_saveexec_b64 s[52:53], s[0:1]
	ds_write_b32 v219, v225 offset:128
	s_or_b64 exec, exec, s[52:53]
	s_waitcnt lgkmcnt(0)
	ds_read_b128 v[102:105], v218 offset:224
	ds_read_b128 v[106:109], v218 offset:192
	ds_read_b128 v[110:113], v218 offset:160
	ds_read_b128 v[114:117], v218 offset:128
	s_waitcnt lgkmcnt(3)
	v_pk_mul_f32 v[48:49], v[48:49], v[104:105]
	s_waitcnt lgkmcnt(2)
	v_pk_mul_f32 v[44:45], v[44:45], v[108:109]
	s_waitcnt lgkmcnt(1)
	v_pk_mul_f32 v[40:41], v[40:41], v[112:113]
	s_waitcnt lgkmcnt(0)
	v_pk_mul_f32 v[36:37], v[36:37], v[116:117]
	v_pk_mul_f32 v[46:47], v[46:47], v[102:103]
	v_pk_mul_f32 v[42:43], v[42:43], v[106:107]
	v_pk_mul_f32 v[38:39], v[38:39], v[110:111]
	v_pk_mul_f32 v[34:35], v[34:35], v[114:115]
	v_pk_mul_f32 v[64:65], v[64:65], v[104:105]
	v_pk_mul_f32 v[60:61], v[60:61], v[108:109]
	v_pk_mul_f32 v[56:57], v[56:57], v[112:113]
	v_pk_mul_f32 v[52:53], v[52:53], v[116:117]
	v_pk_mul_f32 v[62:63], v[62:63], v[102:103]
	v_pk_mul_f32 v[58:59], v[58:59], v[106:107]
	v_pk_mul_f32 v[54:55], v[54:55], v[110:111]
	v_pk_mul_f32 v[50:51], v[50:51], v[114:115]
	v_pk_mul_f32 v[32:33], v[32:33], v[104:105]
	v_pk_mul_f32 v[28:29], v[28:29], v[108:109]
	v_pk_mul_f32 v[24:25], v[24:25], v[112:113]
	v_pk_mul_f32 v[20:21], v[20:21], v[116:117]
	v_pk_mul_f32 v[30:31], v[30:31], v[102:103]
	v_pk_mul_f32 v[26:27], v[26:27], v[106:107]
	v_pk_mul_f32 v[22:23], v[22:23], v[110:111]
	v_pk_mul_f32 v[18:19], v[18:19], v[114:115]
	v_pk_mul_f32 v[16:17], v[16:17], v[104:105]
	v_pk_mul_f32 v[12:13], v[12:13], v[108:109]
	v_pk_mul_f32 v[8:9], v[8:9], v[112:113]
	v_pk_mul_f32 v[4:5], v[4:5], v[116:117]
	v_pk_mul_f32 v[14:15], v[14:15], v[102:103]
	v_pk_mul_f32 v[10:11], v[10:11], v[106:107]
	v_pk_mul_f32 v[6:7], v[6:7], v[110:111]
	v_pk_mul_f32 v[2:3], v[2:3], v[114:115]

; __device__ __forceinline__ void partialSM(f32x16& p0, f32x16& p1, float& m_reg, float& mn, float& alpha) {
;     float pmax = p0[0]; for (int r = 1; r < 16; ++r) pmax = fmaxf(pmax, p0[r]); for (int r = 0; r < 16; ++r) pmax = fmaxf(pmax, p1[r]);
;     { auto rr = __builtin_amdgcn_permlane32_swap(__float_as_uint(pmax), __float_as_uint(pmax), false, false);
;       pmax = fmaxf(__uint_as_float(rr[0]), __uint_as_float(rr[1])); }
;     constexpr float C2 = 1.4426950408889634f * SCALE;
;     if (__builtin_expect(__all((pmax - m_reg) * SCALE <= THR), 1)) { mn = m_reg; alpha = 1.f; }
;     else { mn = fmaxf(m_reg, pmax); alpha = __builtin_amdgcn_exp2f((m_reg - mn) * C2); m_reg = mn; }
;     const float mnL = -mn * C2;
;     for (int r = 0; r < 16; ++r) p0[r] = fmaf(p0[r], C2, mnL); for (int r = 0; r < 16; ++r) p1[r] = fmaf(p1[r], C2, mnL);
;     for (int r = 0; r < 16; ++r) p0[r] = __builtin_amdgcn_exp2f(p0[r]);
; }
; __device__ __forceinline__ void finishSM(f32x16& p0, f32x16& p1, float alpha, float& l_reg, bf16x8& pa0, bf16x8& pa1, bf16x8& pa2, bf16x8& pa3) {
;     for (int r = 0; r < 16; ++r) p1[r] = __builtin_amdgcn_exp2f(p1[r]);
;     float ps = 0; for (int r = 0; r < 16; ++r) ps += p0[r]; for (int r = 0; r < 16; ++r) ps += p1[r];
;     { auto rr = __builtin_amdgcn_permlane32_swap(__float_as_uint(ps), __float_as_uint(ps), false, false);
;       ps = __uint_as_float(rr[0]) + __uint_as_float(rr[1]); }
;     l_reg = l_reg * alpha + ps;
;     ...
;     PK4(p0, 0, pa0); PK4(p0, 8, pa1); PK4(p1, 0, pa2); PK4(p1, 8, pa3);
;     ...
; }
; template <int KB, bool SK>
; __device__ __forceinline__ void qkt(f32x16& p0, f32x16& p1, const char* K_lds, int r32, int hi, const bf16x8* qr, bool act) {
;     if (SK && !act) { const float NEG = -__builtin_inff();
; #pragma unroll
;         for (int r = 0; r < 16; ++r) { p0[r] = NEG; p1[r] = NEG; } return; }
;     p0 = f32x16{}; p1 = f32x16{};
;     const char* kb[4];
; #pragma unroll
;     for (int dd = 0; dd < 4; ++dd) kb[dd] = K_lds + KB * SHM_K + KSWZ(r32, (dd * 16 + hi * 8) * 2);
; #pragma unroll
;     for (int d0 = 0; d0 < 8; ++d0) { const char* a = kb[d0 & 3] + (d0 >> 2) * 128;
;         bf16x8 b0 = *reinterpret_cast<const bf16x8*>(a);
;         bf16x8 b1 = *reinterpret_cast<const bf16x8*>(a + 32 * 256);
;         const bf16x8 qf = qr[d0];
;         p0 = __builtin_amdgcn_mfma_f32_32x32x16_bf16(b0, qf, p0, 0, 0, 0);
.Lh2_back:
	v_fmamk_f32 v68, v114, 0x3e0293ee, v253
	v_fmamk_f32 v69, v115, 0x3e0293ee, v253
	s_waitcnt lgkmcnt(12)
	v_mfma_f32_32x32x16_bf16 v[50:65], v[182:185], v[90:93], v[50:65]
	ds_read_b64_tr_b16 v[86:87], v202 offset:0x4600
	ds_read_b64_tr_b16 v[88:89], v202 offset:0x4e00
	v_fmamk_f32 v70, v116, 0x3e0293ee, v253
	v_fmamk_f32 v71, v117, 0x3e0293ee, v253
	v_fmamk_f32 v79, v118, 0x3e0293ee, v253
	v_fmamk_f32 v80, v119, 0x3e0293ee, v253
	s_waitcnt lgkmcnt(12)
	v_mfma_f32_32x32x16_bf16 v[50:65], v[186:189], v[94:97], v[50:65]
	ds_read_b64_tr_b16 v[90:91], v202 offset:0x5600
	ds_read_b64_tr_b16 v[92:93], v202 offset:0x5e00
	v_fmamk_f32 v72, v120, 0x3e0293ee, v253
	v_fmamk_f32 v73, v121, 0x3e0293ee, v253
	v_fmamk_f32 v81, v122, 0x3e0293ee, v253
	v_fmamk_f32 v82, v123, 0x3e0293ee, v253
	s_waitcnt lgkmcnt(12)
	v_mfma_f32_32x32x16_bf16 v[50:65], v[190:193], v[246:249], v[50:65]
	ds_read_b64_tr_b16 v[94:95], v202 offset:0x6600
	ds_read_b64_tr_b16 v[96:97], v202 offset:0x6e00
	v_fmamk_f32 v74, v124, 0x3e0293ee, v253
	v_fmamk_f32 v75, v125, 0x3e0293ee, v253
	v_fmamk_f32 v76, v126, 0x3e0293ee, v253
	v_fmamk_f32 v77, v127, 0x3e0293ee, v253
	s_waitcnt lgkmcnt(12)
	v_mfma_f32_32x32x16_bf16 v[18:33], v[178:181], v[230:233], v[18:33]
	ds_read_b64_tr_b16 v[246:247], v202 offset:0x7600
	ds_read_b64_tr_b16 v[248:249], v202 offset:0x7e00
	v_fmamk_f32 v83, v128, 0x3e0293ee, v253
	v_fmamk_f32 v78, v129, 0x3e0293ee, v253
	v_fmamk_f32 v126, v98, 0x3e0293ee, v253
	v_fmamk_f32 v127, v99, 0x3e0293ee, v253
	s_waitcnt lgkmcnt(12)
	v_mfma_f32_32x32x16_bf16 v[18:33], v[182:185], v[234:237], v[18:33]
	v_fmamk_f32 v124, v100, 0x3e0293ee, v253
	v_fmamk_f32 v125, v101, 0x3e0293ee, v253
	v_fmamk_f32 v120, v102, 0x3e0293ee, v253
	s_waitcnt lgkmcnt(10)
	v_mfma_f32_32x32x16_bf16 v[18:33], v[186:189], v[238:241], v[18:33]
	v_fmamk_f32 v121, v103, 0x3e0293ee, v253
	v_fmamk_f32 v116, v104, 0x3e0293ee, v253
	v_fmamk_f32 v117, v105, 0x3e0293ee, v253
	s_waitcnt lgkmcnt(8)
	v_mfma_f32_32x32x16_bf16 v[18:33], v[190:193], v[242:245], v[18:33]
	v_fmamk_f32 v114, v106, 0x3e0293ee, v253
	v_fmamk_f32 v115, v107, 0x3e0293ee, v253
	v_fmamk_f32 v128, v108, 0x3e0293ee, v253
	s_waitcnt lgkmcnt(6)
	v_mfma_f32_32x32x16_bf16 v[2:17], v[178:181], v[86:89], v[2:17]
	v_fmamk_f32 v129, v109, 0x3e0293ee, v253
	v_fmamk_f32 v122, v110, 0x3e0293ee, v253
	v_fmamk_f32 v123, v111, 0x3e0293ee, v253
	s_waitcnt lgkmcnt(4)
	v_mfma_f32_32x32x16_bf16 v[2:17], v[182:185], v[90:93], v[2:17]
	v_fmamk_f32 v118, v112, 0x3e0293ee, v253
	v_fmamk_f32 v119, v113, 0x3e0293ee, v253
	v_add_f32_e32 v98, v223, v224
	s_waitcnt lgkmcnt(0)
	s_andn2_b64 vcc, exec, s[76:77]
	s_barrier
	s_cbranch_vccnz .Lh2_pvt_nowrite
	s_waitcnt vmcnt(0)
	v_mfma_f32_32x32x16_bf16 v[2:17], v[186:189], v[94:97], v[2:17]
	ds_write_b128 v209, v[162:165] offset:16384
	v_fmac_f32_e32 v98, v197, v221
	v_add_f32_e32 v221, v228, v229
	v_fmac_f32_e32 v221, v98, v225
	v_mfma_f32_32x32x16_bf16 v[2:17], v[190:193], v[246:249], v[2:17]
	ds_write_b128 v210, v[166:169] offset:16384
	s_branch .Lh2_pvt_join
.Lh2_pvt_nowrite:
	v_mfma_f32_32x32x16_bf16 v[2:17], v[186:189], v[94:97], v[2:17]
	v_fmac_f32_e32 v98, v197, v221
	v_add_f32_e32 v221, v228, v229
	v_fmac_f32_e32 v221, v98, v225
	v_mfma_f32_32x32x16_bf16 v[2:17], v[190:193], v[246:249], v[2:17]
